# sliding-window GQA mixer: per-head bias table extended over out-of-window distances (masked entries), 8 lookups per q-tile by immediate offset; fourth q-tile no longer exec-masked serial lookups
# baseline (speedup 1.0000x reference)
; #define LAS __attribute__((address_space(3)))
; __global__ void __launch_bounds__(512, 2) mega_fwd(Args a) {
;     ...
;             {
;                 LAS float* lt = (LAS float*)(lds + AW_LUT);
;                 int t0_ = threadIdx.x; asm volatile("" : "+v"(t0_));
;                 for (int e = t0_; e < 8 * 128; e += 512) lt[e] = relb[(int)T5B[e & 127] * 16 + (e >> 7)] * 1.4426950408889634f;
;                 __syncthreads();
;             }
;             int t1_ = threadIdx.x; asm volatile("" : "+v"(t1_));
;             const int wv = blockIdx.x * 8 + __builtin_amdgcn_readfirstlane(t1_ >> 6), NWV = G * 8;
;             (void)wv; (void)NWV;
;             unsigned* qctr = (unsigned*)a.ws + 8192 + ph;
;             for (;;) {
;                 unsigned v_ = 0u; if ((t1_ & 63) == 0) v_ = atomicAdd(qctr, 1u);
.LBB0_245:
	s_or_b64 exec, exec, s[0:1]
	v_readlane_b32 s0, v255, 30
	v_readlane_b32 s1, v255, 31
	s_lshl_b32 s0, s0, 3
	s_ashr_i32 s1, s0, 31
	v_readlane_b32 s40, v254, 25
	v_mov_b32_e32 v1, v214
	s_lshl_b64 s[0:1], s[0:1], 2
	v_readlane_b32 s42, v254, 27
	v_readlane_b32 s46, v254, 31
	s_waitcnt lgkmcnt(0)
	s_barrier
	v_and_b32_e32 v228, 0x7f, v214
	v_lshrrev_b32_e32 v229, 7, v214
	v_lshlrev_b32_e32 v230, 2, v214
	v_add_u32_e32 v230, 0x12000, v230
	ds_read_b32 v231, v230
	ds_read_b32 v232, v230 offset:2048
	v_lshlrev_b32_e32 v233, 10, v229
	v_lshl_add_u32 v233, v228, 2, v233
	v_add_u32_e32 v233, 0x14000, v233
	v_cmp_lt_u32_e32 vcc, 31, v228
	v_mov_b32_e32 v235, 0x200
	s_nop 0
	v_cndmask_b32_e32 v234, 0, v235, vcc
	v_add_u32_e32 v234, v234, v233
	v_mov_b32_e32 v236, 0xf149f2ca
	s_waitcnt lgkmcnt(0)
	ds_write_b32 v233, v231 offset:128
	ds_write_b32 v233, v232 offset:4224
	ds_write_b32 v234, v236
	ds_write_b32 v234, v236 offset:4096
	s_waitcnt lgkmcnt(0)
	s_barrier
	v_readlane_b32 s41, v254, 26
	v_readlane_b32 s43, v254, 28
	v_readlane_b32 s47, v254, 32
	s_add_u32 s42, s46, s0
	v_and_b32_e32 v1, 63, v1
	s_addc_u32 s43, s47, s1
	v_cmp_eq_u32_e64 s[40:41], 0, v1
	v_readlane_b32 s44, v254, 29
	v_readlane_b32 s45, v254, 30
	v_readlane_b32 s48, v254, 33
	v_readlane_b32 s49, v254, 34
	v_readlane_b32 s50, v254, 35
	v_readlane_b32 s51, v254, 36
	v_readlane_b32 s52, v254, 37
	v_readlane_b32 s53, v254, 38
	v_readlane_b32 s54, v254, 39
	v_readlane_b32 s55, v254, 40
	s_branch .LBB0_249

; template <int MODE>
; __device__ __forceinline__ void attn_wave(LAS unsigned char* lds, const bf16_t* qkv, bf16_t* Yout, const float* sinks, int wi) {
;     ...
;             const int dbase = q0 + QSTEP * qt + c - k0 - 4 * g;
;             if (MODE == MODE_A) {
;                 float mx = -1e30f;
; #pragma unroll
;                 for (int nt = 0; nt < 2; ++nt)
; #pragma unroll
;                     for (int j = 0; j < 4; ++j) { const int dist = dbase - (16 * nt + j); const bool valid = (unsigned)dist < 128u;
;                         const float bias2 = lutp[qt * HSTEP * 128 + (dist & 127)];
;                         const float lg = valid ? (s[nt][j] * C1 + bias2) : -1e30f; s[nt][j] = lg; mx = fmaxf(mx, lg); }
;                 mx = fmaxf(mx, __shfl_xor(mx, 16)); mx = fmaxf(mx, __shfl_xor(mx, 32));
;                 const float mnew = fmaxf(mrun[qt], mx); const float alpha = __builtin_amdgcn_exp2f(mrun[qt] - mnew); mrun[qt] = mnew;
;                 float ps = 0.f;
; #pragma unroll
;                 for (int nt = 0; nt < 2; ++nt)
; #pragma unroll
;                     for (int j = 0; j < 4; ++j) { const float p = __builtin_amdgcn_exp2f(s[nt][j] - mnew); s[nt][j] = p; ps += p; }
;                 lrun[qt] = lrun[qt] * alpha + ps;
; #pragma unroll
;                 for (int dt = 0; dt < 4; ++dt) o[qt][dt] = o[qt][dt] * alpha;
.LBB0_264:
	s_waitcnt vmcnt(3)
	v_mfma_f32_16x16x32_bf16 v[136:139], v[120:123], v[72:75], 0
	s_waitcnt vmcnt(2)
	v_mfma_f32_16x16x32_bf16 v[140:143], v[124:127], v[76:79], v[136:139]
	s_waitcnt vmcnt(1)
	v_mfma_f32_16x16x32_bf16 v[136:139], v[132:135], v[72:75], 0
	s_waitcnt vmcnt(0)
	v_mfma_f32_16x16x32_bf16 v[136:139], v[128:131], v[76:79], v[136:139]
	v_lshlrev_b32_e32 v236, 2, v170
	v_lshl_add_u32 v236, s19, 1, v236
	v_add_u32_e32 v236, 0x140b0, v236
	ds_read_b32 v228, v236 offset:76
	ds_read_b32 v229, v236 offset:72
	ds_read_b32 v230, v236 offset:68
	ds_read_b32 v231, v236 offset:64
	ds_read_b32 v232, v236 offset:12
	ds_read_b32 v233, v236 offset:8
	ds_read_b32 v234, v236 offset:4
	ds_read_b32 v235, v236 offset:0
	v_mov_b32_e32 v237, 0x3e38aa3b
	s_waitcnt lgkmcnt(0)
	v_fma_f32 v173, v140, v237, v228
	v_fma_f32 v172, v141, v237, v229
	v_fma_f32 v141, v142, v237, v230
	v_fma_f32 v140, v143, v237, v231
	v_fma_f32 v143, v136, v237, v232
	v_fma_f32 v142, v137, v237, v233
	v_fma_f32 v137, v138, v237, v234
	v_fma_f32 v136, v139, v237, v235
	v_max3_f32 v138, v173, s86, v172
	v_max3_f32 v138, v138, v141, v140
	v_cmp_lt_i32_e32 vcc, v223, v218
	v_max3_f32 v138, v138, v143, v142
	v_max3_f32 v138, v138, v137, v136
	v_cndmask_b32_e32 v139, v217, v223, vcc
	v_lshlrev_b32_e32 v139, 2, v139
	ds_bpermute_b32 v139, v139, v138
	v_cmp_lt_i32_e32 vcc, v224, v218
	s_waitcnt lgkmcnt(0)
	v_max_f32_e32 v139, v139, v139
	v_max_f32_e32 v138, v138, v139
	v_cndmask_b32_e32 v139, v217, v224, vcc
	v_lshlrev_b32_e32 v139, 2, v139
	ds_bpermute_b32 v139, v139, v138
	s_waitcnt lgkmcnt(0)
	v_max3_f32 v174, v163, v138, v139
	v_sub_f32_e32 v139, v173, v174
	v_exp_f32_e32 v139, v139
	v_sub_f32_e32 v172, v172, v174
	v_exp_f32_e32 v172, v172
	v_sub_f32_e32 v141, v141, v174
	v_exp_f32_e32 v141, v141
	v_sub_f32_e32 v140, v140, v174
	v_exp_f32_e32 v140, v140
	v_sub_f32_e32 v143, v143, v174
	v_sub_f32_e32 v138, v163, v174
	v_add_f32_e32 v163, 0, v139
	v_exp_f32_e32 v143, v143
	v_sub_f32_e32 v142, v142, v174
	v_add_f32_e32 v163, v172, v163
	v_exp_f32_e32 v142, v142
	v_sub_f32_e32 v137, v137, v174
	v_add_f32_e32 v163, v141, v163
	v_exp_f32_e32 v173, v137
	v_add_f32_e32 v163, v140, v163
	v_add_f32_e32 v163, v143, v163
	v_add_f32_e32 v163, v142, v163
	v_sub_f32_e32 v136, v136, v174
	v_add_f32_e32 v137, v173, v163
	v_exp_f32_e32 v163, v136
	v_exp_f32_e32 v136, v138
	v_cvt_pk_bf16_f32 v138, v143, v142
	v_add_f32_e32 v175, v163, v137
	v_fmac_f32_e32 v175, v164, v136
	v_pk_mul_f32 v[58:59], v[58:59], v[136:137] op_sel_hi:[1,0]
	v_pk_mul_f32 v[56:57], v[56:57], v[136:137] op_sel_hi:[1,0]
	v_pk_mul_f32 v[62:63], v[62:63], v[136:137] op_sel_hi:[1,0]
	v_pk_mul_f32 v[60:61], v[60:61], v[136:137] op_sel_hi:[1,0]
	v_pk_mul_f32 v[66:67], v[66:67], v[136:137] op_sel_hi:[1,0]
	v_pk_mul_f32 v[64:65], v[64:65], v[136:137] op_sel_hi:[1,0]
	v_pk_mul_f32 v[70:71], v[70:71], v[136:137] op_sel_hi:[1,0]
	v_pk_mul_f32 v[68:69], v[68:69], v[136:137] op_sel_hi:[1,0]
	v_cvt_pk_bf16_f32 v136, v139, v172
	v_cvt_pk_bf16_f32 v137, v141, v140
	v_cvt_pk_bf16_f32 v139, v173, v163
	v_mov_b32_e32 v164, v175
	v_mov_b32_e32 v163, v174
	v_mfma_f32_16x16x32_bf16 v[56:59], v[116:119], v[136:139], v[56:59]
	v_mfma_f32_16x16x32_bf16 v[60:63], v[112:115], v[136:139], v[60:63]
	v_mfma_f32_16x16x32_bf16 v[64:67], v[108:111], v[136:139], v[64:67]
	v_mfma_f32_16x16x32_bf16 v[68:71], v[104:107], v[136:139], v[68:71]
	s_and_b64 vcc, exec, s[4:5]
	s_cbranch_vccnz .LBB0_262
.LBB0_281:
	s_waitcnt vmcnt(3)
	v_mfma_f32_16x16x32_bf16 v[136:139], v[120:123], v[80:83], 0
	s_waitcnt vmcnt(2)
	v_mfma_f32_16x16x32_bf16 v[140:143], v[124:127], v[84:87], v[136:139]
	s_waitcnt vmcnt(1)
	v_mfma_f32_16x16x32_bf16 v[136:139], v[132:135], v[80:83], 0
	s_waitcnt vmcnt(0)
	v_mfma_f32_16x16x32_bf16 v[136:139], v[128:131], v[84:87], v[136:139]
	v_lshlrev_b32_e32 v236, 2, v170
	v_lshl_add_u32 v236, s19, 1, v236
	v_add_u32_e32 v236, 0x140b0, v236
	ds_read_b32 v228, v236 offset:1100
	ds_read_b32 v229, v236 offset:1096
	ds_read_b32 v230, v236 offset:1092
	ds_read_b32 v231, v236 offset:1088
	ds_read_b32 v232, v236 offset:1036
	ds_read_b32 v233, v236 offset:1032
	ds_read_b32 v234, v236 offset:1028
	ds_read_b32 v235, v236 offset:1024
	v_mov_b32_e32 v237, 0x3e38aa3b
	s_waitcnt lgkmcnt(0)
	v_fma_f32 v173, v140, v237, v228
	v_fma_f32 v172, v141, v237, v229
	v_fma_f32 v141, v142, v237, v230
	v_fma_f32 v140, v143, v237, v231
	v_fma_f32 v143, v136, v237, v232
	v_fma_f32 v142, v137, v237, v233
	v_fma_f32 v137, v138, v237, v234
	v_fma_f32 v136, v139, v237, v235
	v_max3_f32 v138, v173, s86, v172
	v_max3_f32 v138, v138, v141, v140
	v_cmp_lt_i32_e32 vcc, v223, v218
	v_max3_f32 v138, v138, v143, v142
	v_max3_f32 v138, v138, v137, v136
	v_cndmask_b32_e32 v139, v217, v223, vcc
	v_lshlrev_b32_e32 v139, 2, v139
	ds_bpermute_b32 v139, v139, v138
	v_cmp_lt_i32_e32 vcc, v224, v218
	s_waitcnt lgkmcnt(0)
	v_max_f32_e32 v139, v139, v139
	v_max_f32_e32 v138, v138, v139
	v_cndmask_b32_e32 v139, v217, v224, vcc
	v_lshlrev_b32_e32 v139, 2, v139
	ds_bpermute_b32 v139, v139, v138
	s_waitcnt lgkmcnt(0)
	v_max3_f32 v174, v162, v138, v139
	v_sub_f32_e32 v139, v173, v174
	v_exp_f32_e32 v139, v139
	v_sub_f32_e32 v172, v172, v174
	v_exp_f32_e32 v172, v172
	v_sub_f32_e32 v141, v141, v174
	v_exp_f32_e32 v141, v141
	v_sub_f32_e32 v140, v140, v174
	v_exp_f32_e32 v140, v140
	v_sub_f32_e32 v143, v143, v174
	v_sub_f32_e32 v138, v162, v174
	v_add_f32_e32 v162, 0, v139
	v_exp_f32_e32 v143, v143
	v_sub_f32_e32 v142, v142, v174
	v_add_f32_e32 v162, v172, v162
	v_exp_f32_e32 v142, v142
	v_sub_f32_e32 v137, v137, v174
	v_add_f32_e32 v162, v141, v162
	v_exp_f32_e32 v173, v137
	v_add_f32_e32 v162, v140, v162
	v_add_f32_e32 v162, v143, v162
	v_add_f32_e32 v162, v142, v162
	v_sub_f32_e32 v136, v136, v174
	v_add_f32_e32 v137, v173, v162
	v_exp_f32_e32 v162, v136
	v_exp_f32_e32 v136, v138
	v_cvt_pk_bf16_f32 v138, v143, v142
	v_add_f32_e32 v175, v162, v137
	v_fmac_f32_e32 v175, v161, v136
	v_pk_mul_f32 v[42:43], v[42:43], v[136:137] op_sel_hi:[1,0]
	v_pk_mul_f32 v[40:41], v[40:41], v[136:137] op_sel_hi:[1,0]
	v_pk_mul_f32 v[46:47], v[46:47], v[136:137] op_sel_hi:[1,0]
	v_pk_mul_f32 v[44:45], v[44:45], v[136:137] op_sel_hi:[1,0]
	v_pk_mul_f32 v[50:51], v[50:51], v[136:137] op_sel_hi:[1,0]
	v_pk_mul_f32 v[48:49], v[48:49], v[136:137] op_sel_hi:[1,0]
	v_pk_mul_f32 v[54:55], v[54:55], v[136:137] op_sel_hi:[1,0]
	v_pk_mul_f32 v[52:53], v[52:53], v[136:137] op_sel_hi:[1,0]
	v_cvt_pk_bf16_f32 v136, v139, v172
	v_cvt_pk_bf16_f32 v137, v141, v140
	v_cvt_pk_bf16_f32 v139, v173, v162
	v_mov_b32_e32 v161, v175
	v_mov_b32_e32 v162, v174
	v_mfma_f32_16x16x32_bf16 v[40:43], v[116:119], v[136:139], v[40:43]
	v_mfma_f32_16x16x32_bf16 v[44:47], v[112:115], v[136:139], v[44:47]
	v_mfma_f32_16x16x32_bf16 v[48:51], v[108:111], v[136:139], v[48:51]
	v_mfma_f32_16x16x32_bf16 v[52:55], v[104:107], v[136:139], v[52:55]
	s_and_b64 vcc, exec, s[4:5]
	s_cbranch_vccnz .LBB0_263
; template <int MODE>
; __device__ __forceinline__ void attn_wave(LAS unsigned char* lds, const bf16_t* qkv, bf16_t* Yout, const float* sinks, int wi) {
;     ...
;             const int dbase = q0 + QSTEP * qt + c - k0 - 4 * g;
;             if (MODE == MODE_A) {
;                 float mx = -1e30f;
; #pragma unroll
;                 for (int nt = 0; nt < 2; ++nt)
; #pragma unroll
;                     for (int j = 0; j < 4; ++j) { const int dist = dbase - (16 * nt + j); const bool valid = (unsigned)dist < 128u;
;                         const float bias2 = lutp[qt * HSTEP * 128 + (dist & 127)];
;                         const float lg = valid ? (s[nt][j] * C1 + bias2) : -1e30f; s[nt][j] = lg; mx = fmaxf(mx, lg); }
;                 mx = fmaxf(mx, __shfl_xor(mx, 16)); mx = fmaxf(mx, __shfl_xor(mx, 32));
;                 const float mnew = fmaxf(mrun[qt], mx); const float alpha = __builtin_amdgcn_exp2f(mrun[qt] - mnew); mrun[qt] = mnew;
;                 float ps = 0.f;
; #pragma unroll
;                 for (int nt = 0; nt < 2; ++nt)
; #pragma unroll
;                     for (int j = 0; j < 4; ++j) { const float p = __builtin_amdgcn_exp2f(s[nt][j] - mnew); s[nt][j] = p; ps += p; }
;                 lrun[qt] = lrun[qt] * alpha + ps;
; #pragma unroll
;                 for (int dt = 0; dt < 4; ++dt) o[qt][dt] = o[qt][dt] * alpha;
.LBB0_298:
	s_waitcnt vmcnt(3)
	v_mfma_f32_16x16x32_bf16 v[136:139], v[120:123], v[88:91], 0
	s_waitcnt vmcnt(2)
	v_mfma_f32_16x16x32_bf16 v[140:143], v[124:127], v[92:95], v[136:139]
	s_waitcnt vmcnt(1)
	v_mfma_f32_16x16x32_bf16 v[136:139], v[132:135], v[88:91], 0
	s_waitcnt vmcnt(0)
	v_mfma_f32_16x16x32_bf16 v[136:139], v[128:131], v[92:95], v[136:139]
	v_lshlrev_b32_e32 v236, 2, v170
	v_lshl_add_u32 v236, s19, 1, v236
	v_add_u32_e32 v236, 0x140b0, v236
	ds_read_b32 v228, v236 offset:2124
	ds_read_b32 v229, v236 offset:2120
	ds_read_b32 v230, v236 offset:2116
	ds_read_b32 v231, v236 offset:2112
	ds_read_b32 v232, v236 offset:2060
	ds_read_b32 v233, v236 offset:2056
	ds_read_b32 v234, v236 offset:2052
	ds_read_b32 v235, v236 offset:2048
	v_mov_b32_e32 v237, 0x3e38aa3b
	s_waitcnt lgkmcnt(0)
	v_fma_f32 v173, v140, v237, v228
	v_fma_f32 v172, v141, v237, v229
	v_fma_f32 v141, v142, v237, v230
	v_fma_f32 v140, v143, v237, v231
	v_fma_f32 v143, v136, v237, v232
	v_fma_f32 v142, v137, v237, v233
	v_fma_f32 v137, v138, v237, v234
	v_fma_f32 v136, v139, v237, v235
	v_max3_f32 v138, v173, s86, v172
	v_max3_f32 v138, v138, v141, v140
	v_cmp_lt_i32_e32 vcc, v223, v218
	v_max3_f32 v138, v138, v143, v142
	v_max3_f32 v138, v138, v137, v136
	v_cndmask_b32_e32 v139, v217, v223, vcc
	v_lshlrev_b32_e32 v139, 2, v139
	ds_bpermute_b32 v139, v139, v138
	v_cmp_lt_i32_e32 vcc, v224, v218
	s_waitcnt lgkmcnt(0)
	v_max_f32_e32 v139, v139, v139
	v_max_f32_e32 v138, v138, v139
	v_cndmask_b32_e32 v139, v217, v224, vcc
	v_lshlrev_b32_e32 v139, 2, v139
	ds_bpermute_b32 v139, v139, v138
	s_waitcnt lgkmcnt(0)
	v_max3_f32 v174, v159, v138, v139
	v_sub_f32_e32 v139, v173, v174
	v_exp_f32_e32 v139, v139
	v_sub_f32_e32 v172, v172, v174
	v_exp_f32_e32 v172, v172
	v_sub_f32_e32 v141, v141, v174
	v_exp_f32_e32 v141, v141
	v_sub_f32_e32 v140, v140, v174
	v_exp_f32_e32 v140, v140
	v_sub_f32_e32 v143, v143, v174
	v_sub_f32_e32 v138, v159, v174
	v_add_f32_e32 v159, 0, v139
	v_exp_f32_e32 v143, v143
	v_sub_f32_e32 v142, v142, v174
	v_add_f32_e32 v159, v172, v159
	v_exp_f32_e32 v142, v142
	v_sub_f32_e32 v137, v137, v174
	v_add_f32_e32 v159, v141, v159
	v_exp_f32_e32 v173, v137
	v_add_f32_e32 v159, v140, v159
	v_add_f32_e32 v159, v143, v159
	v_add_f32_e32 v159, v142, v159
	v_sub_f32_e32 v136, v136, v174
	v_add_f32_e32 v137, v173, v159
	v_exp_f32_e32 v159, v136
	v_exp_f32_e32 v136, v138
	v_cvt_pk_bf16_f32 v138, v143, v142
	v_add_f32_e32 v175, v159, v137
	v_fmac_f32_e32 v175, v158, v136
	v_pk_mul_f32 v[26:27], v[26:27], v[136:137] op_sel_hi:[1,0]
	v_pk_mul_f32 v[24:25], v[24:25], v[136:137] op_sel_hi:[1,0]
	v_pk_mul_f32 v[30:31], v[30:31], v[136:137] op_sel_hi:[1,0]
	v_pk_mul_f32 v[28:29], v[28:29], v[136:137] op_sel_hi:[1,0]
	v_pk_mul_f32 v[34:35], v[34:35], v[136:137] op_sel_hi:[1,0]
	v_pk_mul_f32 v[32:33], v[32:33], v[136:137] op_sel_hi:[1,0]
	v_pk_mul_f32 v[38:39], v[38:39], v[136:137] op_sel_hi:[1,0]
	v_pk_mul_f32 v[36:37], v[36:37], v[136:137] op_sel_hi:[1,0]
	v_cvt_pk_bf16_f32 v136, v139, v172
	v_cvt_pk_bf16_f32 v137, v141, v140
	v_cvt_pk_bf16_f32 v139, v173, v159
	v_mov_b32_e32 v158, v175
	v_mov_b32_e32 v159, v174
	v_mfma_f32_16x16x32_bf16 v[24:27], v[116:119], v[136:139], v[24:27]
	v_mfma_f32_16x16x32_bf16 v[28:31], v[112:115], v[136:139], v[28:31]
	v_mfma_f32_16x16x32_bf16 v[32:35], v[108:111], v[136:139], v[32:35]
	v_mfma_f32_16x16x32_bf16 v[36:39], v[104:107], v[136:139], v[36:39]
	s_and_b64 vcc, exec, s[4:5]
	s_cbranch_vccnz .LBB0_259
.LBB0_315:
	s_waitcnt vmcnt(3)
	v_mfma_f32_16x16x32_bf16 v[120:123], v[120:123], v[96:99], 0
	s_waitcnt vmcnt(2)
	v_mfma_f32_16x16x32_bf16 v[124:127], v[124:127], v[100:103], v[120:123]
	s_waitcnt vmcnt(1)
	v_mfma_f32_16x16x32_bf16 v[120:123], v[132:135], v[96:99], 0
	s_waitcnt vmcnt(0)
	v_mfma_f32_16x16x32_bf16 v[120:123], v[128:131], v[100:103], v[120:123]
	v_lshlrev_b32_e32 v236, 2, v170
	v_lshl_add_u32 v236, s19, 1, v236
	v_add_u32_e32 v236, 0x140b0, v236
	ds_read_b32 v228, v236 offset:3148
	ds_read_b32 v229, v236 offset:3144
	ds_read_b32 v230, v236 offset:3140
	ds_read_b32 v231, v236 offset:3136
	ds_read_b32 v232, v236 offset:3084
	ds_read_b32 v233, v236 offset:3080
	ds_read_b32 v234, v236 offset:3076
	ds_read_b32 v235, v236 offset:3072
	v_mov_b32_e32 v237, 0x3e38aa3b
	s_waitcnt lgkmcnt(0)
	v_fma_f32 v133, v124, v237, v228
	v_fma_f32 v132, v125, v237, v229
	v_fma_f32 v125, v126, v237, v230
	v_fma_f32 v124, v127, v237, v231
	v_fma_f32 v127, v120, v237, v232
	v_fma_f32 v126, v121, v237, v233
	v_fma_f32 v121, v122, v237, v234
	v_fma_f32 v120, v123, v237, v235
	s_branch .LBB0_258
